# f32 matrix cores for the RWKV state update: state held transposed in MFMA accumulator tiles, rank-2 update via v_mfma_f32_32x32x2_f32, dots via pk_fma on half-k per lane, 3x fewer LDS reads
# speedup vs baseline: 1.0312x; 1.0282x over previous
.LBB0_380:
	s_and_b32 s20, s75, 63
	s_and_b64 s[2:3], s[34:35], exec
	s_movk_i32 s2, 0x1000
	s_cselect_b32 s19, 0x100, s2
	s_lshr_b32 s77, s19, 3
	s_and_saveexec_b64 s[2:3], s[50:51]
	s_xor_b64 s[16:17], exec, s[2:3]
	s_cbranch_execz .LBB0_392
	s_waitcnt vmcnt(2)
	v_mov_b32_e32 v0, 0
	s_andn2_b64 vcc, exec, s[0:1]
	v_mov_b32_e32 v1, 0
	v_mov_b32_e32 v2, 0
	v_mov_b32_e32 v3, 0
	s_waitcnt vmcnt(0)
	v_mov_b32_e32 v4, 0
	v_mov_b32_e32 v5, 0
	v_mov_b32_e32 v6, 0
	v_mov_b32_e32 v7, 0
	v_mov_b32_e32 v8, 0
	v_mov_b32_e32 v9, 0
	v_mov_b32_e32 v10, 0
	v_mov_b32_e32 v11, 0
	v_mov_b32_e32 v12, 0
	v_mov_b32_e32 v13, 0
	v_mov_b32_e32 v14, 0
	v_mov_b32_e32 v15, 0
	v_mov_b32_e32 v16, 0
	v_mov_b32_e32 v17, 0
	v_mov_b32_e32 v18, 0
	v_mov_b32_e32 v19, 0
	v_mov_b32_e32 v20, 0
	v_mov_b32_e32 v21, 0
	v_mov_b32_e32 v22, 0
	v_mov_b32_e32 v23, 0
	v_mov_b32_e32 v24, 0
	v_mov_b32_e32 v25, 0
	v_mov_b32_e32 v26, 0
	v_mov_b32_e32 v27, 0
	v_mov_b32_e32 v28, 0
	v_mov_b32_e32 v29, 0
	v_mov_b32_e32 v30, 0
	v_mov_b32_e32 v31, 0
	v_mov_b32_e32 v32, 0
	v_mov_b32_e32 v33, 0
	v_mov_b32_e32 v34, 0
	v_mov_b32_e32 v35, 0
	v_mov_b32_e32 v36, 0
	v_mov_b32_e32 v37, 0
	v_mov_b32_e32 v38, 0
	v_mov_b32_e32 v39, 0
	v_mov_b32_e32 v40, 0
	v_mov_b32_e32 v41, 0
	v_mov_b32_e32 v42, 0
	v_mov_b32_e32 v43, 0
	v_mov_b32_e32 v44, 0
	v_mov_b32_e32 v45, 0
	v_mov_b32_e32 v46, 0
	v_mov_b32_e32 v47, 0
	v_mov_b32_e32 v48, 0
	v_mov_b32_e32 v49, 0
	v_mov_b32_e32 v50, 0
	v_mov_b32_e32 v51, 0
	v_mov_b32_e32 v52, 0
	v_mov_b32_e32 v53, 0
	v_mov_b32_e32 v54, 0
	v_mov_b32_e32 v55, 0
	v_mov_b32_e32 v56, 0
	v_mov_b32_e32 v57, 0
	v_mov_b32_e32 v58, 0
	v_mov_b32_e32 v59, 0
	v_mov_b32_e32 v60, 0
	v_mov_b32_e32 v61, 0
	v_mov_b32_e32 v62, 0
	v_mov_b32_e32 v63, 0
	s_cbranch_vccnz .LBB0_383
	v_or_b32_e32 v0, s20, v199
	v_lshl_add_u32 v0, s18, 8, v0
	v_ashrrev_i32_e32 v1, 31, v0
	v_lshlrev_b64 v[0:1], 14, v[0:1]
	v_lshl_add_u64 v[64:65], v[150:151], 0, v[0:1]
	v_lshrrev_b32_e32 v68, 7, v173
	v_mul_u32_u24_e32 v68, 0x1ff0, v68
	v_sub_u32_e32 v68, 0, v68
	v_ashrrev_i32_e32 v69, 31, v68
	v_lshl_add_u64 v[64:65], v[64:65], 0, v[68:69]
	v_mov_b32_e32 v68, 0x2000
	v_mov_b32_e32 v69, 0
	v_lshl_add_u64 v[66:67], v[64:65], 0, v[68:69]
	global_load_dwordx4 v[0:3], v[64:65], off offset:0
	global_load_dwordx4 v[4:7], v[64:65], off offset:32
	global_load_dwordx4 v[8:11], v[64:65], off offset:64
	global_load_dwordx4 v[12:15], v[64:65], off offset:96
	global_load_dwordx4 v[16:19], v[64:65], off offset:128
	global_load_dwordx4 v[20:23], v[64:65], off offset:160
	global_load_dwordx4 v[24:27], v[64:65], off offset:192
	global_load_dwordx4 v[28:31], v[64:65], off offset:224
	global_load_dwordx4 v[32:35], v[66:67], off offset:0
	global_load_dwordx4 v[36:39], v[66:67], off offset:32
	global_load_dwordx4 v[40:43], v[66:67], off offset:64
	global_load_dwordx4 v[44:47], v[66:67], off offset:96
	global_load_dwordx4 v[48:51], v[66:67], off offset:128
	global_load_dwordx4 v[52:55], v[66:67], off offset:160
	global_load_dwordx4 v[56:59], v[66:67], off offset:192
	global_load_dwordx4 v[60:63], v[66:67], off offset:224

.LBB0_385:
	s_cmp_ge_u32 s0, s77
	s_cbranch_scc1 .LBB0_384
	v_cndmask_b32_e64 v64, 0, 1, s[90:91]
	s_lshl_b32 s1, s0, 1
	v_lshl_add_u32 v152, v64, 12, v200
	v_and_or_b32 v64, s1, 2, v171
	v_mul_u32_u24_e32 v204, 0x3000, v64
	v_lshrrev_b32_e32 v207, 7, v173
	v_and_b32_e32 v240, 0x7c, v173
	v_lshl_add_u32 v240, v207, 8, v240
	v_add_u32_e32 v241, v204, v173
	v_add_u32_e32 v240, v204, v240
	v_lshl_add_u32 v207, v207, 4, v204
	ds_read_b128 v[64:67], v207 offset:256
	ds_read_b128 v[68:71], v207 offset:288
	ds_read_b128 v[72:75], v207 offset:320
	ds_read_b128 v[76:79], v207 offset:352
	ds_read_b128 v[80:83], v207 offset:384
	ds_read_b128 v[84:87], v207 offset:416
	ds_read_b128 v[88:91], v207 offset:448
	ds_read_b128 v[92:95], v207 offset:480
	ds_read_b128 v[96:99], v207 offset:0
	ds_read_b128 v[100:103], v207 offset:32
	ds_read_b128 v[104:107], v207 offset:64
	ds_read_b128 v[108:111], v207 offset:96
	ds_read_b128 v[112:115], v207 offset:128
	ds_read_b128 v[116:119], v207 offset:160
	ds_read_b128 v[120:123], v207 offset:192
	ds_read_b128 v[124:127], v207 offset:224
	ds_read_b32 v224, v240 offset:512
	ds_read_b32 v225, v240 offset:640
	ds_read_b32 v226, v241 offset:1280
	ds_read_b128 v[128:131], v207 offset:1024
	ds_read_b128 v[132:135], v207 offset:1056
	ds_read_b128 v[136:139], v207 offset:1088
	ds_read_b128 v[140:143], v207 offset:1120
	ds_read_b128 v[208:211], v207 offset:1152
	ds_read_b128 v[212:215], v207 offset:1184
	ds_read_b128 v[216:219], v207 offset:1216
	ds_read_b128 v[220:223], v207 offset:1248
	s_waitcnt vmcnt(0)
	s_mov_b32 s1, 0
.LBB0_387:
	s_waitcnt lgkmcnt(14)
	v_pk_fma_f32 v[228:229], v[0:1], v[64:65], 0 op_sel_hi:[1,1,0]
	v_pk_fma_f32 v[230:231], v[32:33], v[64:65], 0 op_sel_hi:[1,1,0]
	v_pk_fma_f32 v[228:229], v[2:3], v[66:67], v[228:229]
	v_pk_fma_f32 v[230:231], v[34:35], v[66:67], v[230:231]
	v_pk_fma_f32 v[228:229], v[4:5], v[68:69], v[228:229]
	v_pk_fma_f32 v[230:231], v[36:37], v[68:69], v[230:231]
	v_pk_fma_f32 v[228:229], v[6:7], v[70:71], v[228:229]
	v_pk_fma_f32 v[230:231], v[38:39], v[70:71], v[230:231]
	v_pk_fma_f32 v[228:229], v[8:9], v[72:73], v[228:229]
	v_pk_fma_f32 v[230:231], v[40:41], v[72:73], v[230:231]
	v_pk_fma_f32 v[228:229], v[10:11], v[74:75], v[228:229]
	v_pk_fma_f32 v[230:231], v[42:43], v[74:75], v[230:231]
	v_pk_fma_f32 v[228:229], v[12:13], v[76:77], v[228:229]
	v_pk_fma_f32 v[230:231], v[44:45], v[76:77], v[230:231]
	v_pk_fma_f32 v[228:229], v[14:15], v[78:79], v[228:229]
	v_pk_fma_f32 v[230:231], v[46:47], v[78:79], v[230:231]
	v_pk_fma_f32 v[228:229], v[16:17], v[80:81], v[228:229]
	v_pk_fma_f32 v[230:231], v[48:49], v[80:81], v[230:231]
	v_pk_fma_f32 v[228:229], v[18:19], v[82:83], v[228:229]
	v_pk_fma_f32 v[230:231], v[50:51], v[82:83], v[230:231]
	v_pk_fma_f32 v[228:229], v[20:21], v[84:85], v[228:229]
	v_pk_fma_f32 v[230:231], v[52:53], v[84:85], v[230:231]
	v_pk_fma_f32 v[228:229], v[22:23], v[86:87], v[228:229]
	v_pk_fma_f32 v[230:231], v[54:55], v[86:87], v[230:231]
	v_pk_fma_f32 v[228:229], v[24:25], v[88:89], v[228:229]
	v_pk_fma_f32 v[230:231], v[56:57], v[88:89], v[230:231]
	v_pk_fma_f32 v[228:229], v[26:27], v[90:91], v[228:229]
	v_pk_fma_f32 v[230:231], v[58:59], v[90:91], v[230:231]
	v_pk_fma_f32 v[228:229], v[28:29], v[92:93], v[228:229]
	v_pk_fma_f32 v[230:231], v[60:61], v[92:93], v[230:231]
	v_pk_fma_f32 v[228:229], v[30:31], v[94:95], v[228:229]
	v_pk_fma_f32 v[230:231], v[62:63], v[94:95], v[230:231]
	v_add_f32_e32 v232, v228, v229
	v_add_f32_e32 v233, v230, v231
	ds_read_b128 v[64:67], v207 offset:1792
	ds_read_b128 v[68:71], v207 offset:1824
	ds_read_b128 v[72:75], v207 offset:1856
	ds_read_b128 v[76:79], v207 offset:1888
	ds_read_b128 v[80:83], v207 offset:1920
	ds_read_b128 v[84:87], v207 offset:1952
	ds_read_b128 v[88:91], v207 offset:1984
	ds_read_b128 v[92:95], v207 offset:2016
	v_permlane32_swap_b32_e32 v232, v233
	v_add_f32_e32 v232, v232, v233
	v_pk_mul_f32 v[0:1], v[0:1], v[96:97]
	v_pk_mul_f32 v[2:3], v[2:3], v[98:99]
	s_waitcnt lgkmcnt(14)
	v_permlane32_swap_b32_e32 v232, v226
	v_pk_mul_f32 v[4:5], v[4:5], v[100:101]
	v_pk_mul_f32 v[6:7], v[6:7], v[102:103]
	v_pk_mul_f32 v[8:9], v[8:9], v[104:105]
	v_pk_mul_f32 v[10:11], v[10:11], v[106:107]
	v_pk_mul_f32 v[12:13], v[12:13], v[108:109]
	v_pk_mul_f32 v[14:15], v[14:15], v[110:111]
	v_pk_mul_f32 v[16:17], v[16:17], v[112:113]
	v_pk_mul_f32 v[18:19], v[18:19], v[114:115]
	v_mfma_f32_32x32x2_f32 v[0:15], v224, v232, v[0:15]
	v_pk_mul_f32 v[20:21], v[20:21], v[116:117]
	v_pk_mul_f32 v[22:23], v[22:23], v[118:119]
	v_pk_mul_f32 v[24:25], v[24:25], v[120:121]
	v_pk_mul_f32 v[26:27], v[26:27], v[122:123]
	v_pk_mul_f32 v[28:29], v[28:29], v[124:125]
	v_pk_mul_f32 v[30:31], v[30:31], v[126:127]
	v_pk_mul_f32 v[32:33], v[32:33], v[96:97]
	v_pk_mul_f32 v[34:35], v[34:35], v[98:99]
	v_mfma_f32_32x32x2_f32 v[16:31], v225, v232, v[16:31]
	v_pk_mul_f32 v[36:37], v[36:37], v[100:101]
	v_pk_mul_f32 v[38:39], v[38:39], v[102:103]
	v_pk_mul_f32 v[40:41], v[40:41], v[104:105]
	v_pk_mul_f32 v[42:43], v[42:43], v[106:107]
	v_pk_mul_f32 v[44:45], v[44:45], v[108:109]
	v_pk_mul_f32 v[46:47], v[46:47], v[110:111]
	v_pk_mul_f32 v[48:49], v[48:49], v[112:113]
	v_pk_mul_f32 v[50:51], v[50:51], v[114:115]
	v_mfma_f32_32x32x2_f32 v[32:47], v224, v226, v[32:47]
	v_pk_mul_f32 v[52:53], v[52:53], v[116:117]
	v_pk_mul_f32 v[54:55], v[54:55], v[118:119]
	v_pk_mul_f32 v[56:57], v[56:57], v[120:121]
	v_pk_mul_f32 v[58:59], v[58:59], v[122:123]
	v_pk_mul_f32 v[60:61], v[60:61], v[124:125]
	v_pk_mul_f32 v[62:63], v[62:63], v[126:127]
	ds_read_b128 v[96:99], v207 offset:1536
	ds_read_b128 v[100:103], v207 offset:1568
	ds_read_b128 v[104:107], v207 offset:1600
	ds_read_b128 v[108:111], v207 offset:1632
	v_mfma_f32_32x32x2_f32 v[48:63], v225, v226, v[48:63]
	ds_read_b128 v[112:115], v207 offset:1664
	ds_read_b128 v[116:119], v207 offset:1696
	ds_read_b128 v[120:123], v207 offset:1728
	ds_read_b128 v[124:127], v207 offset:1760
	ds_read_b32 v224, v240 offset:2048
	ds_read_b32 v225, v240 offset:2176
	ds_read_b32 v226, v241 offset:2816
	v_pk_fma_f32 v[234:235], v[0:1], v[128:129], 0 op_sel_hi:[1,1,0]
	v_pk_fma_f32 v[236:237], v[32:33], v[128:129], 0 op_sel_hi:[1,1,0]
	v_pk_fma_f32 v[234:235], v[2:3], v[130:131], v[234:235]
	v_pk_fma_f32 v[236:237], v[34:35], v[130:131], v[236:237]
	v_pk_fma_f32 v[234:235], v[4:5], v[132:133], v[234:235]
	v_pk_fma_f32 v[236:237], v[36:37], v[132:133], v[236:237]
	v_pk_fma_f32 v[234:235], v[6:7], v[134:135], v[234:235]
	v_pk_fma_f32 v[236:237], v[38:39], v[134:135], v[236:237]
	s_waitcnt lgkmcnt(14)
	v_pk_fma_f32 v[234:235], v[8:9], v[136:137], v[234:235]
	v_pk_fma_f32 v[236:237], v[40:41], v[136:137], v[236:237]
	v_pk_fma_f32 v[234:235], v[10:11], v[138:139], v[234:235]
	v_pk_fma_f32 v[236:237], v[42:43], v[138:139], v[236:237]
	v_pk_fma_f32 v[234:235], v[12:13], v[140:141], v[234:235]
	v_pk_fma_f32 v[236:237], v[44:45], v[140:141], v[236:237]
	v_pk_fma_f32 v[234:235], v[14:15], v[142:143], v[234:235]
	v_pk_fma_f32 v[236:237], v[46:47], v[142:143], v[236:237]
	v_pk_fma_f32 v[234:235], v[16:17], v[208:209], v[234:235]
	v_pk_fma_f32 v[236:237], v[48:49], v[208:209], v[236:237]
	v_pk_fma_f32 v[234:235], v[18:19], v[210:211], v[234:235]
	v_pk_fma_f32 v[236:237], v[50:51], v[210:211], v[236:237]
	v_pk_fma_f32 v[234:235], v[20:21], v[212:213], v[234:235]
	v_pk_fma_f32 v[236:237], v[52:53], v[212:213], v[236:237]
	v_pk_fma_f32 v[234:235], v[22:23], v[214:215], v[234:235]
	v_pk_fma_f32 v[236:237], v[54:55], v[214:215], v[236:237]
	v_pk_fma_f32 v[234:235], v[24:25], v[216:217], v[234:235]
	v_pk_fma_f32 v[236:237], v[56:57], v[216:217], v[236:237]
	v_pk_fma_f32 v[234:235], v[26:27], v[218:219], v[234:235]
	v_pk_fma_f32 v[236:237], v[58:59], v[218:219], v[236:237]
	v_pk_fma_f32 v[234:235], v[28:29], v[220:221], v[234:235]
	v_pk_fma_f32 v[236:237], v[60:61], v[220:221], v[236:237]
	v_pk_fma_f32 v[234:235], v[30:31], v[222:223], v[234:235]
	v_pk_fma_f32 v[236:237], v[62:63], v[222:223], v[236:237]
	v_add_f32_e32 v238, v234, v235
	v_add_f32_e32 v239, v236, v237
	ds_read_b128 v[128:131], v207 offset:2560
	ds_read_b128 v[132:135], v207 offset:2592
	ds_read_b128 v[136:139], v207 offset:2624
	ds_read_b128 v[140:143], v207 offset:2656
	ds_read_b128 v[208:211], v207 offset:2688
	ds_read_b128 v[212:215], v207 offset:2720
	ds_read_b128 v[216:219], v207 offset:2752
	ds_read_b128 v[220:223], v207 offset:2784
	v_permlane32_swap_b32_e32 v238, v239
	v_add_u32_e32 v242, s1, v152
	v_add_f32_e32 v238, v238, v239
	s_addk_i32 s1, 0x100
	v_add_u32_e32 v204, 0x600, v204
	v_add_u32_e32 v207, 0x600, v207
	v_add_u32_e32 v240, 0x600, v240
	v_add_u32_e32 v241, 0x600, v241
	s_cmpk_lg_i32 s1, 0x800
	ds_write_b32 v242, v238
	s_cbranch_scc1 .LBB0_387
	s_branch .LBB0_384

.LBB0_390:
	s_and_b64 vcc, exec, s[34:35]
	s_cbranch_vccz .LBB0_392
	v_lshl_or_b32 v64, s18, 8, v172
	v_or_b32_e32 v64, s20, v64
	v_ashrrev_i32_e32 v65, 31, v64
	v_lshlrev_b64 v[64:65], 14, v[64:65]
	v_lshl_add_u64 v[64:65], v[158:159], 0, v[64:65]
	v_lshrrev_b32_e32 v68, 7, v173
	v_mul_u32_u24_e32 v68, 0x1ff0, v68
	v_sub_u32_e32 v68, 0, v68
	v_ashrrev_i32_e32 v69, 31, v68
	v_lshl_add_u64 v[64:65], v[64:65], 0, v[68:69]
	v_mov_b32_e32 v68, 0x2000
	v_mov_b32_e32 v69, 0
	v_lshl_add_u64 v[66:67], v[64:65], 0, v[68:69]
	global_store_dwordx4 v[64:65], v[0:3], off offset:0
	global_store_dwordx4 v[64:65], v[4:7], off offset:32
	global_store_dwordx4 v[64:65], v[8:11], off offset:64
	global_store_dwordx4 v[64:65], v[12:15], off offset:96
	global_store_dwordx4 v[64:65], v[16:19], off offset:128
	global_store_dwordx4 v[64:65], v[20:23], off offset:160
	global_store_dwordx4 v[64:65], v[24:27], off offset:192
	global_store_dwordx4 v[64:65], v[28:31], off offset:224
	global_store_dwordx4 v[66:67], v[32:35], off offset:0
	global_store_dwordx4 v[66:67], v[36:39], off offset:32
	global_store_dwordx4 v[66:67], v[40:43], off offset:64
	global_store_dwordx4 v[66:67], v[44:47], off offset:96
	global_store_dwordx4 v[66:67], v[48:51], off offset:128
	global_store_dwordx4 v[66:67], v[52:55], off offset:160
	global_store_dwordx4 v[66:67], v[56:59], off offset:192
	global_store_dwordx4 v[66:67], v[60:63], off offset:224
